# MIX_O scan: block-id rotation so the 4 row-group items of a head share an XCD (L2 reuse of r/k/v/w/a loads)
# speedup vs baseline: 1.0188x; 1.0188x over previous
; #define LAS __attribute__((address_space(3)))
; __device__ __forceinline__ unsigned char* WSP() { return (unsigned char*)IN(41); }
; __device__ __forceinline__ int TID() { int t = threadIdx.x; asm volatile("" : "+v"(t)); return t; }
; __device__ __forceinline__ int BID() { int b = blockIdx.x; asm volatile("" : "+s"(b)); return b; }
; __device__ __forceinline__ int GSZ() { int g = gridDim.x; asm volatile("" : "+s"(g)); return g; }
; __device__ __forceinline__ int rfl(int v) { return __builtin_amdgcn_readfirstlane(v); }
;     unsigned char* ws = WSP();
;     LAS float* lds = (LAS float*)lds8;
;     const int tid = TID(), wave = rfl(tid >> 6), lane = tid & 63, bid = BID(), gsz = GSZ();
;     const bool consumer = wave < 4;
;     const float* R_ = (const float*)(ws + WS_R); const float* K_ = (const float*)(ws + WS_K);
;     const float* V_ = (const float*)(ws + (li == 0 ? WS_VF : WS_V3)); const float* VF_ = (const float*)(ws + WS_VF);
;     const float* W2O = (const float*)(ws + WS_W2O); const float* A2O = (const float*)(ws + WS_A2O); const float* V2O = (const float*)(ws + WS_V2O);
;     float* Y_ = (float*)(ws + WS_MIX); float* BONUS = (float*)(ws + WS_XA);
;     const float* PROJ = (const float*)(ws + WS_PROJ); float* OPART = (float*)(ws + WS_OPART);
;     const int ptid = tid & 255, tt = ptid >> 4, c4 = ptid & 15;
;     f32x4 raw[2][7], cp[6];
;     ScanDesc pd; pd.ok = 0;
;     int lit = it0 + bid, lc = 0;
;     const int rg = lane >> 4, cl = lane & 15, crow = (wave & 3) * 4 + rg;
;     f32x2 s01 = (f32x2){0.f, 0.f}, s23 = s01; f32x4 snext = (f32x4){0.f, 0.f, 0.f, 0.f};
;     ...
;     __syncthreads();
;     int cit = it0 + bid, cc = 0;
;     if (!consumer) { P_LOAD(); P_PUT(lds); P_LOAD(); }
;     else { const ScanDesc d0 = scan_desc<RW>(cit, cc); if (d0.ok && d0.samp) C_S0(d0, snext); }
.LBB0_902:
	s_movk_i32 s2, 0x148
	s_ashr_i32 s3, s2, 31
	s_add_u32 s2, s0, s2
	s_addc_u32 s3, s1, s3
	v_mov_b32_e32 v76, v146
	s_mov_b32 s4, s67
	s_load_dwordx2 s[24:25], s[2:3], 0x0
	s_load_dwordx2 s[6:7], s[0:1], 0x150
	v_readfirstlane_b32 s2, v76
	s_ashr_i32 s2, s2, 6
	s_cmp_gt_i32 s2, 3
	v_bfe_u32 v0, v76, 4, 2
	s_waitcnt lgkmcnt(0)
	s_mov_b32 s5, s6
	s_cselect_b64 s[6:7], -1, 0
	s_cmp_lt_i32 s2, 4
	s_cselect_b64 s[8:9], -1, 0
	s_cmp_lg_u32 s5, 0x100
	s_cbranch_scc1 .Lmo_noperm
	s_and_b32 s4, s67, 7
	s_lshl_b32 s4, s4, 5
	s_lshr_b32 s3, s67, 3
	s_or_b32 s4, s4, s3
.Lmo_noperm:
	s_add_u32 s10, s24, 0x27800000
	v_writelane_b32 v234, s6, 56
	s_addc_u32 s11, s25, 0
	s_add_u32 s12, s24, 0x2ba00000
	v_writelane_b32 v234, s7, 57
	s_addc_u32 s13, s25, 0
	v_readlane_b32 s3, v234, 31
	s_add_u32 s14, s24, s3
	s_addc_u32 s15, s25, 0
	s_add_u32 s16, s24, 0x17000000
	s_addc_u32 s17, s25, 0
	s_add_u32 s18, s24, 0x1b200000
	s_addc_u32 s19, s25, 0
	s_add_u32 s20, s24, 0x1f400000
	s_addc_u32 s21, s25, 0
	s_add_u32 s22, s24, 0x23600000
	s_addc_u32 s23, s25, 0
	s_add_u32 s26, s24, 0x6800000
	s_addc_u32 s27, s25, 0
	s_lshl_b32 s2, s2, 2
	v_and_b32_e32 v124, 15, v76
	v_and_or_b32 v126, s2, 12, v0
	s_mov_b64 s[6:7], -1
	s_and_b64 vcc, exec, s[8:9]
	s_barrier
	s_cbranch_vccz .LBB0_905
	s_add_i32 s2, s4, 0xffffff00
	s_cmpk_gt_u32 s2, 0xfff
	s_cbranch_scc1 .LBB0_931
	s_lshl_b32 s3, s4, 4
	s_mov_b32 s6, 40
	s_and_b32 s3, s3, 48
	s_bfe_u32 s28, s4, 0x50002
	s_ashr_i32 s7, s6, 31
	s_add_u32 s6, s0, s6
	s_addc_u32 s7, s1, s7
	s_lshr_b32 s2, s2, 2
	s_and_b32 s2, s2, 0x3e0
	v_readlane_b32 s30, v234, 32
	s_or_b32 s2, s2, s30
	s_load_dwordx2 s[6:7], s[6:7], 0x0
	s_or_b32 s2, s2, s28
	s_lshl_b32 s2, s2, 6
	s_or_b32 s2, s2, s3
	v_or_b32_e32 v2, s2, v126
	v_lshlrev_b64 v[0:1], 8, v[2:3]
	s_waitcnt lgkmcnt(0)
	v_lshl_add_u64 v[0:1], s[6:7], 0, v[0:1]
	v_lshlrev_b32_e32 v2, 4, v124
	v_lshl_add_u64 v[0:1], v[0:1], 0, v[2:3]
	global_load_dwordx4 v[72:75], v[0:1], off
	s_mov_b64 s[6:7], 0
